# scan-v8-a0fast-bhoist
# speedup vs baseline: 1.0394x; 1.0068x over previous
.LBB0_500:
	v_writelane_b32 v255, s80, 6
	v_writelane_b32 v255, s78, 4
	s_nop 1
	v_writelane_b32 v255, s79, 5
	v_writelane_b32 v255, s72, 7
	v_writelane_b32 v255, s97, 8
	s_or_b64 exec, exec, s[4:5]
	s_mov_b64 s[6:7], s[76:77]
	v_writelane_b32 v255, s71, 9
	s_cmpk_gt_i32 s71, 0xff
	s_barrier
	s_cbranch_scc1 .LBB0_614
	s_bfe_u32 s0, s70, 0x20006
	s_lshl_b32 s69, s0, 6
	s_cmpk_gt_u32 s70, 0xff
	v_or_b32_e32 v2, s69, v252
	s_cselect_b64 s[4:5], -1, 0
	v_lshlrev_b32_e32 v2, 7, v2
	s_or_b32 s73, s69, 0x100
	v_and_b32_e32 v141, 0x7c00, v2
	v_or_b32_e32 v2, s73, v252
	v_lshlrev_b32_e32 v2, 7, v2
	s_or_b32 s74, s69, 0x200
	v_and_b32_e32 v142, 0xfc00, v2
	v_or_b32_e32 v2, s74, v252
	s_movk_i32 s1, 0x20f
	v_mov_b32_e32 v3, 0xfffffdf0
	v_cmp_lt_u32_e32 vcc, s1, v2
	v_bfrev_b32_e32 v4, 64
	s_or_b32 s75, s69, 0x300
	v_cndmask_b32_e32 v3, 0, v3, vcc
	v_add_lshl_u32 v2, v3, v2, 7
	v_cndmask_b32_e32 v4, 0, v4, vcc
	v_and_b32_e32 v2, 0xfffffc00, v2
	v_add_u32_e32 v143, v2, v4
	v_or_b32_e32 v2, s75, v252
	v_mov_b32_e32 v3, 0x7ffef800
	v_lshl_add_u32 v2, v2, 7, v3
	v_and_b32_e32 v2, 0xfc00, v2
	s_or_b32 s76, s69, 0x400
	v_or_b32_e32 v144, 0x2000000, v2
	v_or_b32_e32 v2, s76, v252
	v_mul_u32_u24_e32 v3, 0x3e1, v2
	v_lshrrev_b32_e32 v3, 19, v3
	v_mul_i32_i24_e32 v4, 0xfffffdf0, v3
	v_add_lshl_u32 v2, v4, v2, 7
	v_and_b32_e32 v2, 0xfffffc00, v2
	s_or_b32 s77, s69, 0x500
	v_lshl_add_u32 v145, v3, 25, v2
	v_or_b32_e32 v2, s77, v252
	v_mov_b32_e32 v3, 0x7ffdf000
	v_lshl_add_u32 v2, v2, 7, v3
	v_and_b32_e32 v2, 0xfc00, v2
	s_or_b32 s78, s69, 0x600
	v_or_b32_e32 v146, 0x4000000, v2
	v_or_b32_e32 v2, s78, v252
	s_movk_i32 s79, 0x630
	v_cmp_gt_u32_e32 vcc, s79, v2
	s_and_b64 s[8:9], s[4:5], vcc
	v_writelane_b32 v255, s8, 2
	v_and_b32_e32 v6, 48, v252
	v_and_b32_e32 v3, 15, v0
	v_writelane_b32 v255, s9, 3
	v_lshrrev_b32_e32 v4, 4, v252
	v_readlane_b32 s17, v255, 7
	s_cmp_eq_u32 s17, 7
	s_cselect_b64 s[8:9], -1, 0
	s_lshr_b32 s1, s70, 7
	s_lshl_b32 s80, s1, 4
	s_add_i32 s2, s69, 0xf0
	s_lshl_b32 s1, s1, 6
	v_writelane_b32 v255, s2, 10
	s_add_i32 s2, s1, 0
	v_add_u32_e32 v148, s2, v6
	s_lshl_b32 s2, s17, 5
	s_and_b32 s16, s2, 32
	v_lshl_or_b32 v5, v4, 2, s80
	v_lshrrev_b32_e32 v8, 2, v0
	s_lshl_b32 s82, s0, 4
	v_or_b32_e32 v150, s16, v3
	s_movk_i32 s0, 0x44
	v_or_b32_e32 v7, s1, v3
	v_bitop3_b32 v8, v4, v8, 3 bitop3:0x78
	s_add_i32 s1, 0, 0x12540
	v_mul_lo_u32 v9, v5, s0
	v_or_b32_e32 v12, 16, v150
	v_lshl_add_u32 v149, v8, 4, s1
	v_bitop3_b32 v8, v4, v0, 7 bitop3:0x78
	v_add_u32_e32 v10, v9, v150
	v_bitop3_b32 v1, v4, v1, 4 bitop3:0x36
	v_add_u32_e32 v9, v9, v12
	v_lshlrev_b32_e32 v6, 1, v3
	v_cmp_eq_u32_e64 s[14:15], 3, v4
	v_lshlrev_b32_e32 v8, 4, v8
	v_lshl_add_u32 v151, v10, 2, 0
	v_lshlrev_b32_e32 v10, 7, v150
	v_lshlrev_b32_e32 v1, 4, v1
	v_lshl_add_u32 v153, v9, 2, 0
	v_lshlrev_b32_e32 v9, 7, v12
	v_lshlrev_b32_e32 v4, 5, v4
	v_or_b32_e32 v11, v10, v8
	v_or_b32_e32 v10, v10, v1
	v_or_b32_e32 v8, v9, v8
	v_or_b32_e32 v1, v9, v1
	v_lshlrev_b32_e32 v9, 6, v5
	v_bitop3_b32 v4, s16, v4, v6 bitop3:0x36
	v_and_or_b32 v4, v4, 56, v9
	v_or_b32_e32 v9, v4, v191
	v_lshlrev_b32_e32 v9, 1, v9
	s_add_i32 s89, 0, 0x12540
	s_add_i32 s90, 0, 0x16540
	s_add_i32 s91, 0, 0x18540
	s_add_i32 s92, 0, 0x14540
	v_add_u32_e32 v154, s89, v9
	v_add_u32_e32 v155, s90, v9
	v_add_u32_e32 v156, s91, v9
	v_add_u32_e32 v157, s92, v9
	v_or_b32_e32 v9, 1, v5
	v_lshlrev_b32_e32 v12, 6, v9
	v_lshlrev_b32_e32 v9, 3, v9
	v_bitop3_b32 v9, v9, s16, v6 bitop3:0x1e
	v_and_or_b32 v9, v9, 56, v12
	v_or_b32_e32 v12, v9, v191
	v_lshlrev_b32_e32 v12, 1, v12
	v_add_u32_e32 v158, s89, v12
	v_add_u32_e32 v159, s90, v12
	v_add_u32_e32 v160, s91, v12
	v_add_u32_e32 v161, s92, v12
	v_or_b32_e32 v12, 2, v5
	v_lshlrev_b32_e32 v13, 6, v12
	v_lshlrev_b32_e32 v12, 3, v12
	v_bitop3_b32 v12, v12, s16, v6 bitop3:0x1e
	v_and_or_b32 v12, v12, 56, v13
	v_or_b32_e32 v13, v12, v191
	v_lshlrev_b32_e32 v13, 1, v13
	v_or_b32_e32 v5, 3, v5
	v_add_u32_e32 v162, s89, v13
	v_add_u32_e32 v163, s90, v13
	v_add_u32_e32 v164, s91, v13
	v_add_u32_e32 v165, s92, v13
	v_lshlrev_b32_e32 v13, 6, v5
	v_lshlrev_b32_e32 v5, 3, v5
	v_bitop3_b32 v5, v5, s16, v6 bitop3:0x1e
	v_and_or_b32 v5, v5, 56, v13
	v_or_b32_e32 v6, v5, v191
	v_lshlrev_b32_e32 v6, 1, v6
	v_add_u32_e32 v166, s89, v6
	v_add_u32_e32 v167, s90, v6
	v_add_u32_e32 v168, s91, v6
	v_add_u32_e32 v169, s92, v6
	v_or_b32_e32 v6, s16, v7
	v_lshlrev_b32_e32 v170, 6, v6
	v_lshl_add_u32 v171, v6, 2, 0
	v_or_b32_e32 v6, 4, v191
	v_or_b32_e32 v4, v4, v6
	s_lshl_b32 s84, s17, 4
	v_lshlrev_b32_e32 v4, 1, v4
	s_load_dwordx4 s[16:19], s[6:7], 0xa8
	v_add_u32_e32 v172, s89, v4
	v_add_u32_e32 v173, s90, v4
	v_add_u32_e32 v174, s91, v4
	v_add_u32_e32 v175, s92, v4
	v_or_b32_e32 v4, v9, v6
	v_lshlrev_b32_e32 v4, 1, v4
	s_add_i32 s88, s2, 0
	v_add_u32_e32 v176, s89, v4
	v_add_u32_e32 v177, s90, v4
	v_add_u32_e32 v178, s91, v4
	v_add_u32_e32 v179, s92, v4
	v_or_b32_e32 v4, v12, v6
	s_add_i32 s83, s69, 0
	s_add_i32 s85, s88, 0x20540
	s_add_i32 s86, s88, 0x20d40
	s_add_i32 s87, s88, 0x21540
	s_add_i32 s88, s88, 0x21d40
	v_lshlrev_b32_e32 v4, 1, v4
	v_add_u32_e32 v180, s89, v4
	v_add_u32_e32 v181, s90, v4
	v_add_u32_e32 v182, s91, v4
	v_add_u32_e32 v183, s92, v4
	v_or_b32_e32 v4, v5, v6
	s_waitcnt lgkmcnt(0)
	s_add_u32 s93, s16, 0x20000
	v_mov_b32_e32 v5, 0x1f000
	v_add_u32_e32 v193, 0, v1
	v_mbcnt_lo_u32_b32 v1, -1, 0
	v_lshlrev_b32_e32 v4, 1, v4
	s_addc_u32 s94, s17, 0
	v_lshl_add_u32 v2, v2, 7, v5
	s_add_i32 s0, 0, 0x4000
	v_mbcnt_hi_u32_b32 v1, -1, v1
	v_add_u32_e32 v184, s89, v4
	v_add_u32_e32 v185, s90, v4
	v_add_u32_e32 v186, s91, v4
	v_add_u32_e32 v187, s92, v4
	v_or_b32_e32 v4, 0x400, v170
	v_and_b32_e32 v2, 0x1fc00, v2
	v_writelane_b32 v255, s0, 11
	s_mov_b32 s55, 0x20000
	v_and_or_b32 v1, v1, 64, v3
	v_and_b32_e32 v140, 0x70, v195
	s_mov_b32 s67, 0
	v_xor_b32_e32 v147, 0x1f8, v190
	v_cmp_gt_u32_e64 s[10:11], 16, v252
	v_cmp_lt_u32_e64 s[12:13], 31, v252
	v_lshl_add_u32 v152, v150, 2, 0
	v_or_b32_e32 v188, 0x4000000, v2
	s_mov_b32 s68, 0xbfb8aa3b
	s_mov_b32 s96, 0x2aaaaaab
	s_movk_i32 s97, 0xc0
	s_movk_i32 s64, 0x680
	s_mov_b32 s54, 0x4200400
	s_mov_b32 s26, 0x10000
	s_mov_b32 s58, 0x10000
	s_mov_b32 s59, s55
	v_mov_b32_e32 v5, 0
	s_movk_i32 s65, 0x208
	s_movk_i32 s34, 0x41f
	s_mov_b32 s62, 0x7ffffff0
	s_mov_b32 s63, s55
	s_mov_b32 s35, 0x10540
	v_add_u32_e32 v189, 0, v11
	v_add_u32_e32 v191, 0, v10
	v_add_u32_e32 v192, 0, v8
	s_mov_b32 s70, 0xbf60028a
	v_add_u32_e32 v194, v149, v4
	v_mov_b32_e32 v195, 0x3a27c5ac
	v_mov_b32_e32 v196, 1
	s_add_i32 s72, 0, 0x1ed40
	s_add_i32 s71, 0, 0x1f540
	s_add_i32 s33, 0, 0x1e540
	v_bfrev_b32_e32 v197, -2
	v_mov_b32_e32 v198, 0x9e20
	v_mov_b32_e32 v199, 0x5800
	v_mov_b32_e32 v200, 0x12800000
	v_mov_b32_e32 v201, 0x10800000
	v_lshlrev_b32_e32 v202, 2, v1
	v_lshrrev_b32_e32 v241, 2, v252
	v_lshrrev_b32_e32 v242, 4, v252
	v_and_b32_e32 v243, 3, v252
	v_xor_b32_e32 v242, v242, v243
	v_lshlrev_b32_e32 v242, 4, v242
	v_lshl_add_u32 v241, v241, 6, v242
	v_add_u32_e32 v253, 0x12540, v241
	v_lshl_add_u32 v241, s82, 8, v253
	v_lshrrev_b32_e32 v242, 3, v0
	v_and_b32_e32 v243, 7, v0
	v_lshlrev_b32_e32 v243, 3, v243
	v_lshrrev_b32_e32 v240, 2, v242
	v_and_b32_e32 v242, 3, v242
	v_lshlrev_b32_e32 v242, 1, v242
	v_or_b32_e32 v2, 0, v243
	v_and_b32_e32 v3, 15, v2
	v_xor_b32_e32 v3, v240, v3
	v_lshlrev_b32_e32 v3, 3, v3
	v_lshl_add_u32 v2, v2, 7, v3
	v_add_u32_e32 v244, v2, v242
	v_or_b32_e32 v2, 1, v243
	v_and_b32_e32 v3, 15, v2
	v_xor_b32_e32 v3, v240, v3
	v_lshlrev_b32_e32 v3, 3, v3
	v_lshl_add_u32 v2, v2, 7, v3
	v_add_u32_e32 v245, v2, v242
	v_or_b32_e32 v2, 2, v243
	v_and_b32_e32 v3, 15, v2
	v_xor_b32_e32 v3, v240, v3
	v_lshlrev_b32_e32 v3, 3, v3
	v_lshl_add_u32 v2, v2, 7, v3
	v_add_u32_e32 v246, v2, v242
	v_or_b32_e32 v2, 3, v243
	v_and_b32_e32 v3, 15, v2
	v_xor_b32_e32 v3, v240, v3
	v_lshlrev_b32_e32 v3, 3, v3
	v_lshl_add_u32 v2, v2, 7, v3
	v_add_u32_e32 v247, v2, v242
	v_or_b32_e32 v2, 4, v243
	v_and_b32_e32 v3, 15, v2
	v_xor_b32_e32 v3, v240, v3
	v_lshlrev_b32_e32 v3, 3, v3
	v_lshl_add_u32 v2, v2, 7, v3
	v_add_u32_e32 v248, v2, v242
	v_or_b32_e32 v2, 5, v243
	v_and_b32_e32 v3, 15, v2
	v_xor_b32_e32 v3, v240, v3
	v_lshlrev_b32_e32 v3, 3, v3
	v_lshl_add_u32 v2, v2, 7, v3
	v_add_u32_e32 v249, v2, v242
	v_or_b32_e32 v2, 6, v243
	v_and_b32_e32 v3, 15, v2
	v_xor_b32_e32 v3, v240, v3
	v_lshlrev_b32_e32 v3, 3, v3
	v_lshl_add_u32 v2, v2, 7, v3
	v_add_u32_e32 v250, v2, v242
	v_or_b32_e32 v2, 7, v243
	v_and_b32_e32 v3, 15, v2
	v_xor_b32_e32 v3, v240, v3
	v_lshlrev_b32_e32 v3, 3, v3
	v_lshl_add_u32 v2, v2, 7, v3
	v_add_u32_e32 v251, v2, v242
	v_and_b32_e32 v2, 63, v0
	v_lshrrev_b32_e32 v3, 6, v0
	v_lshlrev_b32_e32 v240, 10, v3
	v_lshl_add_u32 v234, v2, 1, v240
	v_lshlrev_b32_e32 v3, 1, v3
	v_and_b32_e32 v240, 15, v0
	v_xor_b32_e32 v242, v3, v240
	v_lshlrev_b32_e32 v243, 7, v2
	v_lshl_add_u32 v235, v242, 3, v243
	v_xor_b32_e32 v242, 1, v242
	v_lshl_add_u32 v236, v242, 3, v243
	v_and_b32_e32 v2, 15, v0
	v_bfe_u32 v3, v0, 4, 2
	v_lshlrev_b32_e32 v202, 5, v2
	v_lshl_add_u32 v202, v3, 3, v202
	v_add_u32_e32 v202, 0x1e540, v202
	v_lshlrev_b32_e32 v237, 6, v2
	v_lshl_add_u32 v237, v3, 4, v237
	v_add_u32_e32 v237, 0x1f540, v237
	v_lshrrev_b32_e32 v242, 2, v2
	v_xor_b32_e32 v242, v3, v242
	v_and_b32_e32 v242, 3, v242
	v_lshlrev_b32_e32 v242, 4, v242
	v_lshl_add_u32 v242, v2, 6, v242
	v_add_u32_e32 v242, 0x1a540, v242
	v_lshlrev_b32_e32 v243, 9, v3
	v_lshl_add_u32 v243, v2, 1, v243
	v_add_u32_e32 v243, s85, v243
	v_readlane_b32 s95, v255, 9
	s_branch .LBB0_503

.LBB0_539:
	s_and_b32 s61, s23, 0xffff
	s_add_u32 s40, s22, 0x1000000
	s_addc_u32 s41, s23, 0
	s_and_b64 s[18:19], s[16:17], exec
	s_cselect_b32 s18, 0x780, 64
	s_lshl_b32 s19, s18, 10
	buffer_load_dwordx4 v[62:65], v1, s[52:55], s19 offen
	buffer_load_dwordx4 v[58:61], v203, s[52:55], s19 offen
	buffer_load_dwordx4 v[54:57], v204, s[52:55], s19 offen
	buffer_load_dwordx4 v[50:53], v205, s[52:55], s19 offen
	buffer_load_dwordx4 v[46:49], v206, s[52:55], s19 offen
	buffer_load_dwordx4 v[42:45], v207, s[52:55], s19 offen
	s_lshl_b32 s18, s18, 5
	buffer_load_dwordx4 v[38:41], v208, s[52:55], s19 offen
	buffer_load_dword v212, v209, s[56:59], s18 offen
	s_lshl_b32 s18, s95, 6
	s_lshl_b32 s2, s2, 15
	s_mov_b32 s60, s22
	s_xor_b32 s22, s18, 0x2000
	s_sub_i32 s50, s66, s2
	s_lshl_b32 s0, s0, 2
	s_ashr_i32 s23, s22, 31
	s_add_i32 s50, s50, 0x8000
	s_or_b32 s27, s0, 0xe00000
	s_and_b64 s[24:25], s[16:17], exec
	s_cselect_b32 s0, 0x200, 0
	s_add_i32 s0, s0, 0
	s_and_b64 s[24:25], s[16:17], exec
	s_cselect_b32 s19, 0, 0x200
	s_add_i32 s28, s19, 0
	s_or_b32 s29, s2, s66
	s_ashr_i32 s19, s18, 31
	s_lshl_b64 s[22:23], s[22:23], 2
	s_add_u32 s42, s93, s22
	s_addc_u32 s43, s94, s23
	s_lshl_b64 s[18:19], s[18:19], 2
	s_add_u32 s44, s93, s18
	s_addc_u32 s45, s94, s19
	s_lshl_b32 s2, s1, 1
	s_waitcnt vmcnt(12)
	v_lshlrev_b32_e32 v2, 2, v150
	s_add_u32 s46, s40, s2
	v_mov_b32_e32 v22, 0
	s_mov_b32 s51, 0
	v_add_u32_e32 v210, s0, v2
	v_add_u32_e32 v211, s28, v2
	s_addc_u32 s47, s41, 0
	v_mov_b32_e32 v23, v22
	v_mov_b32_e32 v24, v22
	v_mov_b32_e32 v25, v22
	v_mov_b32_e32 v26, v22
	v_mov_b32_e32 v27, v22
	v_mov_b32_e32 v28, v22
	v_mov_b32_e32 v29, v22
	v_mov_b32_e32 v30, v22
	v_mov_b32_e32 v31, v22
	v_mov_b32_e32 v32, v22
	v_mov_b32_e32 v33, v22
	v_mov_b32_e32 v34, v22
	v_mov_b32_e32 v35, v22
	v_mov_b32_e32 v36, v22
	v_mov_b32_e32 v37, v22
	s_waitcnt lgkmcnt(0)
	s_barrier
	v_and_b32_e32 v2, 63, v0
	v_lshlrev_b32_e32 v2, 2, v2
	v_add_u32_e32 v3, s0, v2
	ds_read_b32 v238, v3 offset:17920
	ds_read_b32 v240, v2 offset:18176
	v_add_u32_e32 v3, s28, v2
	ds_read_b32 v254, v3 offset:17920
	s_waitcnt lgkmcnt(0)
	ds_read_b128 v[154:157], v189
	ds_read_b128 v[158:161], v189 offset:8192
	ds_read_b128 v[162:165], v191
	ds_read_b128 v[166:169], v191 offset:8192
	ds_read_b128 v[172:175], v192
	ds_read_b128 v[176:179], v192 offset:8192
	ds_read_b128 v[180:183], v193
	ds_read_b128 v[184:187], v193 offset:8192
	s_waitcnt lgkmcnt(0)
	s_and_b64 vcc, exec, s[4:5]
	s_cbranch_vccz .La0_setup_done
	v_add_u32_e32 v66, s69, v252
	v_lshrrev_b32_e32 v67, 3, v66
	v_and_b32_e32 v68, 7, v66
	v_lshlrev_b32_e32 v69, 5, v68
	v_lshlrev_b32_e32 v68, 4, v68
	v_mov_b32_e32 v70, 0x16540
	v_add_u32_e32 v71, 0, v67
	v_sub_u32_e32 v72, 65, v71
	v_cndmask_b32_e64 v71, v71, v72, s[16:17]
	v_mul_u32_u24_e32 v71, 0x110, v71
	v_add_u32_e32 v71, v71, v69
	v_add_u32_e32 v22, 0x5800, v71
	v_add_u32_e32 v71, 32, v67
	v_sub_u32_e32 v72, 65, v71
	v_cndmask_b32_e64 v71, v71, v72, s[16:17]
	v_mul_u32_u24_e32 v71, 0x110, v71
	v_add_u32_e32 v71, v71, v69
	v_add_u32_e32 v23, 0x5800, v71
	v_add_u32_e32 v71, 64, v67
	v_sub_u32_e32 v72, 65, v71
	v_cndmask_b32_e64 v71, v71, v72, s[16:17]
	v_mul_u32_u24_e32 v71, 0x110, v71
	v_add_u32_e32 v71, v71, v69
	v_add_u32_e32 v73, 0x5800, v71
	v_subrev_u32_e32 v71, 2, v67
	v_sub_u32_e32 v72, 65, v71
	v_cndmask_b32_e64 v71, v71, v72, s[16:17]
	v_mul_u32_u24_e32 v71, 0x110, v71
	v_add_u32_e32 v71, v71, v69
	v_add_u32_e32 v24, 0x9e20, v71
	v_cmp_gt_u32_e32 vcc, 16, v66
	s_nop 1
	v_cndmask_b32_e32 v24, v24, v73, vcc
	v_add_u32_e32 v71, 30, v67
	v_sub_u32_e32 v72, 65, v71
	v_cndmask_b32_e64 v71, v71, v72, s[16:17]
	v_mul_u32_u24_e32 v71, 0x110, v71
	v_add_u32_e32 v71, v71, v69
	v_add_u32_e32 v25, 0x9e20, v71
	v_add_u32_e32 v71, 62, v67
	v_sub_u32_e32 v72, 65, v71
	v_cndmask_b32_e64 v71, v71, v72, s[16:17]
	v_mul_u32_u24_e32 v71, 0x110, v71
	v_add_u32_e32 v71, v71, v69
	v_add_u32_e32 v26, 0x9e20, v71
	v_subrev_u32_e32 v71, 4, v67
	v_sub_u32_e32 v72, 65, v71
	v_cndmask_b32_e64 v71, v71, v72, s[16:17]
	v_mul_u32_u24_e32 v71, 0x80, v71
	v_add_u32_e32 v71, v71, v68
	v_add_u32_e32 v27, 0xe440, v71
	v_cmp_gt_u32_e32 vcc, 32, v66
	s_nop 1
	v_cndmask_b32_e32 v26, v70, v26, vcc
	v_cndmask_b32_e32 v27, v27, v70, vcc
	v_add_u32_e32 v71, 28, v67
	v_sub_u32_e32 v72, 65, v71
	v_cndmask_b32_e64 v71, v71, v72, s[16:17]
	v_mul_u32_u24_e32 v71, 0x80, v71
	v_add_u32_e32 v71, v71, v68
	v_add_u32_e32 v28, 0xe440, v71
	v_add_u32_e32 v71, 60, v67
	v_sub_u32_e32 v72, 65, v71
	v_cndmask_b32_e64 v71, v71, v72, s[16:17]
	v_mul_u32_u24_e32 v71, 0x80, v71
	v_add_u32_e32 v71, v71, v68
	v_add_u32_e32 v29, 0xe440, v71
	v_cmp_gt_u32_e32 vcc, 48, v66
	s_nop 1
	v_cndmask_b32_e32 v29, v70, v29, vcc
	v_lshlrev_b32_e32 v71, 2, v252
	v_add_u32_e32 v71, 0x4f00, v71
	v_cndmask_b32_e64 v30, v70, v71, s[8:9]
.La0_setup_done:
	s_branch .LBB0_541

.LBB0_573:
	s_andn2_saveexec_b64 s[18:19], s[18:19]
	s_or_b64 exec, exec, s[18:19]
	v_lshrrev_b32_e32 v3, 2, v88
	v_cmp_eq_u32_e32 vcc, v2, v3
	s_and_saveexec_b64 s[18:19], vcc
	s_and_b32 s22, s30, 64
	s_lshl_b32 s22, s22, 2
	s_add_i32 s22, s83, s22
	v_lshl_add_u32 v2, v88, 2, s22
	ds_write_b32 v2, v82 offset:20480
	s_or_b64 exec, exec, s[18:19]
	s_andn2_b64 vcc, exec, s[48:49]
	s_cbranch_vccnz .LBB0_605
	s_cmp_eq_u32 s51, 30
	s_cbranch_scc1 .La0_slow
	v_lshlrev_b32_e32 v66, 16, v62
	v_and_b32_e32 v67, 0xffff0000, v62
	v_lshlrev_b32_e32 v68, 16, v63
	v_and_b32_e32 v69, 0xffff0000, v63
	v_lshlrev_b32_e32 v70, 16, v64
	v_and_b32_e32 v71, 0xffff0000, v64
	v_lshlrev_b32_e32 v72, 16, v65
	v_and_b32_e32 v73, 0xffff0000, v65
	ds_write_b128 v22, v[66:69]
	ds_write_b128 v22, v[70:73] offset:16
	v_lshlrev_b32_e32 v74, 16, v58
	v_and_b32_e32 v75, 0xffff0000, v58
	v_lshlrev_b32_e32 v76, 16, v59
	v_and_b32_e32 v77, 0xffff0000, v59
	v_lshlrev_b32_e32 v78, 16, v60
	v_and_b32_e32 v79, 0xffff0000, v60
	v_lshlrev_b32_e32 v80, 16, v61
	v_and_b32_e32 v81, 0xffff0000, v61
	ds_write_b128 v23, v[74:77]
	ds_write_b128 v23, v[78:81] offset:16
	v_lshlrev_b32_e32 v66, 16, v54
	v_and_b32_e32 v67, 0xffff0000, v54
	v_lshlrev_b32_e32 v68, 16, v55
	v_and_b32_e32 v69, 0xffff0000, v55
	v_lshlrev_b32_e32 v70, 16, v56
	v_and_b32_e32 v71, 0xffff0000, v56
	v_lshlrev_b32_e32 v72, 16, v57
	v_and_b32_e32 v73, 0xffff0000, v57
	ds_write_b128 v24, v[66:69]
	ds_write_b128 v24, v[70:73] offset:16
	v_lshlrev_b32_e32 v74, 16, v50
	v_and_b32_e32 v75, 0xffff0000, v50
	v_lshlrev_b32_e32 v76, 16, v51
	v_and_b32_e32 v77, 0xffff0000, v51
	v_lshlrev_b32_e32 v78, 16, v52
	v_and_b32_e32 v79, 0xffff0000, v52
	v_lshlrev_b32_e32 v80, 16, v53
	v_and_b32_e32 v81, 0xffff0000, v53
	ds_write_b128 v25, v[74:77]
	ds_write_b128 v25, v[78:81] offset:16
	v_lshlrev_b32_e32 v66, 16, v46
	v_and_b32_e32 v67, 0xffff0000, v46
	v_lshlrev_b32_e32 v68, 16, v47
	v_and_b32_e32 v69, 0xffff0000, v47
	v_lshlrev_b32_e32 v70, 16, v48
	v_and_b32_e32 v71, 0xffff0000, v48
	v_lshlrev_b32_e32 v72, 16, v49
	v_and_b32_e32 v73, 0xffff0000, v49
	ds_write_b128 v26, v[66:69]
	ds_write_b128 v26, v[70:73] offset:16
	ds_write_b128 v27, v[46:49]
	ds_write_b128 v28, v[42:45]
	ds_write_b128 v29, v[38:41]
	ds_write_b32 v30, v212
	s_branch .LBB0_605
.La0_slow:
	s_cmp_eq_u32 s51, 30
	v_mov_b32_e32 v2, v0
	s_cselect_b64 s[18:19], -1, 0
	s_and_b64 s[22:23], s[16:17], s[18:19]
	v_and_b32_e32 v66, 63, v2
	s_and_b64 s[18:19], s[16:17], exec
	v_and_b32_e32 v68, 7, v2
	v_or_b32_e32 v2, s69, v66
	s_cselect_b32 s2, s2, s81
	v_lshrrev_b32_e32 v3, 3, v2
	s_cmpk_eq_i32 s2, 0x7c0
	v_sub_u32_e32 v4, 0x41, v3
	v_cmp_gt_u32_e32 vcc, 8, v2
	s_cselect_b64 s[18:19], -1, 0
	v_cndmask_b32_e64 v3, v3, v4, s[16:17]
	s_and_b64 s[24:25], s[22:23], vcc
	v_lshlrev_b32_e32 v67, 5, v68
	v_cndmask_b32_e64 v2, v65, 0, s[24:25]
	v_cndmask_b32_e64 v65, v63, 0, s[24:25]
	v_cndmask_b32_e64 v63, v62, 0, s[24:25]
	v_mul_u32_u24_e32 v3, 0x110, v3
	v_cndmask_b32_e64 v4, v64, 0, s[24:25]
	v_add3_u32 v3, 0, v3, v67
	v_lshlrev_b32_e32 v62, 16, v63
	v_and_b32_e32 v63, 0xffff0000, v63
	v_lshlrev_b32_e32 v64, 16, v65
	v_and_b32_e32 v65, 0xffff0000, v65
	ds_write_b128 v3, v[62:65] offset:22528
	v_lshlrev_b32_e32 v64, 16, v2
	v_and_b32_e32 v65, 0xffff0000, v2
	v_or_b32_e32 v2, s73, v66
	v_lshlrev_b32_e32 v62, 16, v4
	v_and_b32_e32 v63, 0xffff0000, v4
	v_lshrrev_b32_e32 v2, 3, v2
	ds_write_b128 v3, v[62:65] offset:22544
	v_sub_u32_e32 v3, 0x41, v2
	v_cndmask_b32_e64 v2, v2, v3, s[16:17]
	v_mul_u32_u24_e32 v2, 0x110, v2
	v_add3_u32 v2, 0, v2, v67
	v_lshlrev_b32_e32 v62, 16, v58
	v_and_b32_e32 v63, 0xffff0000, v58
	v_lshlrev_b32_e32 v64, 16, v59
	v_and_b32_e32 v65, 0xffff0000, v59
	v_lshlrev_b32_e32 v58, 16, v60
	v_and_b32_e32 v59, 0xffff0000, v60
	v_lshlrev_b32_e32 v60, 16, v61
	v_and_b32_e32 v61, 0xffff0000, v61
	ds_write_b128 v2, v[58:61] offset:22544
	v_or_b32_e32 v58, s74, v66
	ds_write_b128 v2, v[62:65] offset:22528
	v_mul_hi_u32_u24_e32 v2, 0x7c1f08, v58
	v_mul_u32_u24_e32 v2, 0x210, v2
	v_sub_u32_e32 v59, v58, v2
	v_cmp_gt_u32_e32 vcc, 8, v59
	s_and_b64 s[24:25], s[22:23], vcc
	s_xor_b64 vcc, s[24:25], -1
	s_and_saveexec_b64 s[48:49], vcc
	v_and_b32_e32 v2, 0x3f8, v59
	v_cmp_eq_u32_e32 vcc, s65, v2
	s_and_b64 vcc, s[18:19], vcc
	s_andn2_b64 s[24:25], s[24:25], exec
	s_and_b64 vcc, vcc, exec
	s_or_b64 s[24:25], s[24:25], vcc
	s_or_b64 exec, exec, s[48:49]
	s_and_saveexec_b64 s[48:49], s[24:25]
	v_mov_b32_e32 v4, v5
	v_mov_b32_e32 v2, v5
	v_mov_b32_e32 v3, v5
	v_mov_b64_e32 v[56:57], v[4:5]
	v_mov_b64_e32 v[54:55], v[2:3]
	s_or_b64 exec, exec, s[48:49]
	v_lshrrev_b32_e32 v2, 3, v59
	s_movk_i32 s2, 0x210
	v_sub_u32_e32 v3, 0x41, v2
	v_cmp_gt_u32_e32 vcc, s2, v58
	v_cndmask_b32_e64 v2, v2, v3, s[16:17]
	v_mul_u32_u24_e32 v2, 0x110, v2
	v_cndmask_b32_e32 v3, v198, v199, vcc
	v_add_u32_e32 v3, 0, v3
	v_add3_u32 v2, v3, v2, v67
	v_lshlrev_b32_e32 v58, 16, v54
	v_and_b32_e32 v59, 0xffff0000, v54
	v_lshlrev_b32_e32 v60, 16, v55
	v_and_b32_e32 v61, 0xffff0000, v55
	v_lshlrev_b32_e32 v54, 16, v56
	v_and_b32_e32 v55, 0xffff0000, v56
	v_lshlrev_b32_e32 v56, 16, v57
	v_and_b32_e32 v57, 0xffff0000, v57
	ds_write_b128 v2, v[58:61]
	ds_write_b128 v2, v[54:57] offset:16
	v_or_b32_e32 v2, s75, v66
	v_mul_hi_u32_u24_e32 v3, 0x7c1f08, v2
	v_mul_u32_u24_e32 v3, 0x210, v3
	v_sub_u32_e32 v54, v2, v3
	v_cmp_gt_u32_e32 vcc, 8, v54
	s_and_b64 s[24:25], s[22:23], vcc
	s_xor_b64 vcc, s[24:25], -1
	s_and_saveexec_b64 s[48:49], vcc
	v_and_b32_e32 v2, 0x3f8, v54
	v_cmp_eq_u32_e32 vcc, s65, v2
	s_and_b64 vcc, s[18:19], vcc
	s_andn2_b64 s[24:25], s[24:25], exec
	s_and_b64 vcc, vcc, exec
	s_or_b64 s[24:25], s[24:25], vcc
	s_or_b64 exec, exec, s[48:49]
	s_and_saveexec_b64 s[48:49], s[24:25]
	v_mov_b32_e32 v4, v5
	v_mov_b32_e32 v2, v5
	v_mov_b32_e32 v3, v5
	v_mov_b64_e32 v[52:53], v[4:5]
	v_mov_b64_e32 v[50:51], v[2:3]
	s_or_b64 exec, exec, s[48:49]
	v_lshrrev_b32_e32 v2, 3, v54
	v_sub_u32_e32 v3, 0x41, v2
	v_cndmask_b32_e64 v2, v2, v3, s[16:17]
	v_mul_u32_u24_e32 v2, 0x110, v2
	v_add3_u32 v2, 0, v2, v67
	v_lshlrev_b32_e32 v54, 16, v50
	v_and_b32_e32 v55, 0xffff0000, v50
	v_lshlrev_b32_e32 v56, 16, v51
	v_and_b32_e32 v57, 0xffff0000, v51
	v_lshlrev_b32_e32 v50, 16, v52
	v_and_b32_e32 v51, 0xffff0000, v52
	v_lshlrev_b32_e32 v52, 16, v53
	v_and_b32_e32 v53, 0xffff0000, v53
	ds_write_b128 v2, v[50:53] offset:40496
	v_or_b32_e32 v51, s76, v66
	ds_write_b128 v2, v[54:57] offset:40480
	v_mul_hi_u32_u24_e32 v2, 0x7c1f08, v51
	v_mul_u32_u24_e32 v2, 0x210, v2
	v_sub_u32_e32 v50, v51, v2
	v_cmp_gt_u32_e32 vcc, 8, v50
	s_and_b64 s[24:25], s[22:23], vcc
	s_xor_b64 vcc, s[24:25], -1
	s_and_saveexec_b64 s[48:49], vcc
	v_and_b32_e32 v2, 0x3f8, v50
	v_cmp_eq_u32_e32 vcc, s65, v2
	s_and_b64 vcc, s[18:19], vcc
	s_andn2_b64 s[24:25], s[24:25], exec
	s_and_b64 vcc, vcc, exec
	s_or_b64 s[24:25], s[24:25], vcc
	s_or_b64 exec, exec, s[48:49]
	s_and_saveexec_b64 s[48:49], s[24:25]
	v_mov_b32_e32 v4, v5
	v_mov_b32_e32 v2, v5
	v_mov_b32_e32 v3, v5
	v_mov_b64_e32 v[48:49], v[4:5]
	v_mov_b64_e32 v[46:47], v[2:3]
	s_or_b64 exec, exec, s[48:49]
	v_lshrrev_b32_e32 v2, 3, v50
	v_sub_u32_e32 v3, 0x41, v2
	v_cndmask_b32_e64 v2, v2, v3, s[16:17]
	v_lshl_add_u32 v50, v68, 4, 0
	v_cmp_lt_u32_e32 vcc, s34, v51
	s_and_saveexec_b64 s[24:25], vcc
	s_xor_b64 s[24:25], exec, s[24:25]
	v_lshl_add_u32 v2, v2, 7, v50
	ds_write_b128 v2, v[46:49] offset:58432
	s_andn2_saveexec_b64 s[24:25], s[24:25]
	s_cbranch_execz .LBB0_596
	v_mul_u32_u24_e32 v2, 0x110, v2
	v_add3_u32 v2, 0, v2, v67
	v_lshlrev_b32_e32 v52, 16, v46
	v_and_b32_e32 v53, 0xffff0000, v46
	v_lshlrev_b32_e32 v54, 16, v47
	v_and_b32_e32 v55, 0xffff0000, v47
	v_lshlrev_b32_e32 v46, 16, v48
	v_and_b32_e32 v47, 0xffff0000, v48
	v_lshlrev_b32_e32 v48, 16, v49
	v_and_b32_e32 v49, 0xffff0000, v49
	ds_write_b128 v2, v[52:55] offset:40480
	ds_write_b128 v2, v[46:49] offset:40496

.LBB0_606:
	s_andn2_b64 vcc, exec, s[18:19]
	s_cbranch_vccnz .LBB0_540
	v_mov_b32_e32 v4, v0
	v_mov_b32_e32 v76, v5
	v_lshrrev_b32_e32 v38, 4, v4
	v_bfe_u32 v135, v4, 4, 2
	v_and_b32_e32 v134, 15, v4
	ds_read_b64_tr_b16 v[50:51], v253
	ds_read_b64_tr_b16 v[52:53], v253 offset:1024
	ds_read_b64_tr_b16 v[54:55], v253 offset:2048
	ds_read_b64_tr_b16 v[56:57], v253 offset:3072
	ds_read_b64_tr_b16 v[58:59], v253 offset:8
	ds_read_b64_tr_b16 v[60:61], v253 offset:1032
	ds_read_b64_tr_b16 v[62:63], v253 offset:2056
	ds_read_b64_tr_b16 v[64:65], v253 offset:3080
	ds_read_b64 v[2:3], v202 offset:2048
	ds_read_b64 v[66:67], v202
	v_or_b32_e32 v41, s84, v134
	v_lshl_add_u32 v139, v41, 7, s31
	v_bitop3_b32 v41, v38, v134, 3 bitop3:0x6c
	v_lshl_add_u32 v41, v41, 3, v139
	ds_read_b128 v[70:73], v237
	ds_read_b64 v[74:75], v41
	ds_read_b128 v[78:81], v242
	ds_read_b128 v[82:85], v242 offset:1024
	ds_read_b128 v[86:89], v242 offset:2048
	ds_read_b128 v[90:93], v242 offset:3072
	v_lshlrev_b32_e32 v212, 4, v135
	s_waitcnt vmcnt(4)
	v_add_u32_e32 v213, 0, v212
	ds_read_b128 v[94:97], v213 offset:20992
	ds_read_b128 v[98:101], v213 offset:21056
	ds_read_b128 v[102:105], v213 offset:21120
	ds_read_b128 v[106:109], v213 offset:21184
	ds_read_b64_tr_b16 v[110:111], v253 offset:4096
	ds_read_b64_tr_b16 v[112:113], v253 offset:5120
	ds_read_b64_tr_b16 v[46:47], v253 offset:6144
	ds_read_b64_tr_b16 v[48:49], v253 offset:7168
	ds_read_b64_tr_b16 v[114:115], v253 offset:4104
	ds_read_b64_tr_b16 v[116:117], v253 offset:5128
	ds_read_b64_tr_b16 v[42:43], v253 offset:6152
	ds_read_b64_tr_b16 v[44:45], v253 offset:7176
	v_bitop3_b32 v4, v135, v134, 4 bitop3:0x36
	v_lshl_add_u32 v68, v4, 3, v139
	v_mov_b32_e32 v4, v5
	v_mov_b32_e32 v77, v5
	v_cvt_pk_bf16_f32 v120, v22, v23
	v_cvt_pk_bf16_f32 v121, v24, v25
	s_waitcnt lgkmcnt(14)
	v_mfma_f32_16x16x32_bf16 v[124:127], v[2:5], v[74:77], 0
	v_cvt_pk_bf16_f32 v122, v26, v27
	v_cvt_pk_bf16_f32 v123, v28, v29
	s_nop 0
	s_nop 0
	v_mfma_f32_16x16x32_bf16 v[50:53], v[50:53], v[120:123], v[124:127]
	v_cvt_pk_bf16_f32 v128, v30, v31
	v_cvt_pk_bf16_f32 v129, v32, v33
	v_cvt_pk_bf16_f32 v130, v34, v35
	v_cvt_pk_bf16_f32 v131, v36, v37
	ds_read_b64 v[118:119], v202 offset:2560
	ds_read_b64 v[38:39], v202 offset:512
	v_mfma_f32_16x16x32_bf16 v[50:53], v[54:57], v[128:131], v[50:53]
	ds_read_b128 v[54:57], v237 offset:1024
	ds_read_b64 v[76:77], v68
	v_mov_b32_e32 v68, v5
	v_mov_b32_e32 v69, v5
	v_mfma_f32_16x16x32_bf16 v[58:61], v[58:61], v[120:123], 0
	s_nop 2
	v_cvt_pk_bf16_f32 v2, v50, v51
	v_cvt_pk_bf16_f32 v3, v52, v53
	v_mov_b32_e32 v120, v5
	v_mfma_f32_16x16x32_bf16 v[58:61], v[62:65], v[128:131], v[58:61]
	v_mov_b32_e32 v121, v5
	v_mfma_f32_16x16x32_bf16 v[50:53], v[66:69], v[2:5], 0
	ds_read_b128 v[62:65], v242 offset:4096
	ds_read_b128 v[66:69], v242 offset:5120
	s_nop 2
	s_nop 2
	v_cvt_pk_bf16_f32 v50, v50, v51
	v_cvt_pk_bf16_f32 v51, v52, v53
	v_mov_b32_e32 v52, v74
	v_mov_b32_e32 v53, v75
	s_nop 0
	s_nop 0
	v_mfma_f32_16x16x32_bf16 v[22:25], v[78:81], v[50:53], v[22:25]
	v_mov_b32_e32 v78, v5
	v_mfma_f32_16x16x32_bf16 v[26:29], v[82:85], v[50:53], v[26:29]
	v_mov_b32_e32 v79, v5
	s_nop 1
	s_waitcnt lgkmcnt(14)
	s_nop 1
	v_pk_mul_f32 v[24:25], v[96:97], v[24:25]
	v_pk_mul_f32 v[22:23], v[94:95], v[22:23]
	v_mfma_f32_16x16x32_bf16 v[30:33], v[86:89], v[50:53], v[30:33]
	ds_read_b128 v[80:83], v242 offset:6144
	ds_read_b128 v[84:87], v242 offset:7168
	ds_read_b128 v[122:125], v213 offset:21248
	ds_read_b128 v[126:129], v213 offset:21312
	v_pk_mul_f32 v[28:29], v[100:101], v[28:29]
	v_mfma_f32_16x16x32_bf16 v[34:37], v[90:93], v[50:53], v[34:37]
	s_nop 0
	s_nop 0
	v_mul_f32_e64 v32, v104, v32
	v_mul_f32_e64 v33, v105, v33
	v_pk_mul_f32 v[30:31], v[102:103], v[30:31]
	ds_read_b128 v[88:91], v213 offset:21376
	ds_read_b128 v[130:133], v213 offset:21440
	v_mfma_f32_16x16x32_bf16 v[50:53], v[70:73], v[50:53], v[58:61]
	v_mul_f32_e64 v26, v98, v26
	v_mul_f32_e64 v27, v99, v27
	v_cvt_pk_bf16_f32 v98, v22, v23
	s_waitcnt lgkmcnt(8)
	v_mfma_f32_16x16x32_bf16 v[102:105], v[118:121], v[76:79], 0
	v_cvt_pk_bf16_f32 v99, v24, v25
	s_nop 1
	v_cvt_pk_bf16_f32 v2, v50, s0
	ds_write_b16 v243, v2
	v_cvt_pk_bf16_f32 v2, v51, s0
	ds_write_b16 v243, v2 offset:128
	v_cvt_pk_bf16_f32 v2, v52, s0
	ds_write_b16 v243, v2 offset:256
	v_cvt_pk_bf16_f32 v2, v53, s0
	v_cvt_pk_bf16_f32 v100, v26, v27
	v_cvt_pk_bf16_f32 v101, v28, v29
	ds_write_b16 v243, v2 offset:384
	s_nop 0
	v_mfma_f32_16x16x32_bf16 v[102:105], v[110:113], v[98:101], v[102:105]
	v_pk_mul_f32 v[36:37], v[108:109], v[36:37]
	v_pk_mul_f32 v[34:35], v[106:107], v[34:35]
	v_cvt_pk_bf16_f32 v106, v30, v31
	v_cvt_pk_bf16_f32 v107, v32, v33
	v_cvt_pk_bf16_f32 v108, v34, v35
	v_cvt_pk_bf16_f32 v109, v36, v37
	ds_read_b64_tr_b16 v[50:51], v253 offset:8192
	ds_read_b64_tr_b16 v[52:53], v253 offset:9216
	ds_read_b64_tr_b16 v[58:59], v253 offset:10240
	ds_read_b64_tr_b16 v[60:61], v253 offset:11264
	v_mfma_f32_16x16x32_bf16 v[46:49], v[46:49], v[106:109], v[102:105]
	v_mov_b32_e32 v40, v5
	v_mov_b32_e32 v41, v5
	ds_read_b64_tr_b16 v[70:71], v253 offset:8200
	ds_read_b64_tr_b16 v[72:73], v253 offset:9224
	ds_read_b64_tr_b16 v[92:93], v253 offset:10248
	ds_read_b64_tr_b16 v[94:95], v253 offset:11272
	v_bitop3_b32 v2, v135, v134, 8 bitop3:0x36
	ds_read_b64 v[74:75], v202 offset:3072
	ds_read_b64 v[96:97], v202 offset:1024
	v_mfma_f32_16x16x32_bf16 v[98:101], v[114:117], v[98:101], 0
	v_lshl_add_u32 v79, v2, 3, v139
	v_cvt_pk_bf16_f32 v2, v46, v47
	v_cvt_pk_bf16_f32 v3, v48, v49
	v_mov_b32_e32 v4, v5
	v_mfma_f32_16x16x32_bf16 v[42:45], v[42:45], v[106:109], v[98:101]
	s_nop 0
	v_mfma_f32_16x16x32_bf16 v[38:41], v[38:41], v[2:5], 0
	s_nop 0
	v_mov_b32_e32 v98, v5
	v_mov_b32_e32 v99, v5
	s_nop 3
	s_nop 0
	v_cvt_pk_bf16_f32 v38, v38, v39
	v_cvt_pk_bf16_f32 v39, v40, v41
	v_mov_b32_e32 v40, v76
	v_mov_b32_e32 v41, v77
	v_mov_b32_e32 v76, v5
	v_mov_b32_e32 v77, v5
	s_waitcnt lgkmcnt(14)
	v_mfma_f32_16x16x32_bf16 v[22:25], v[62:65], v[38:41], v[22:25]
	ds_read_b128 v[46:49], v237 offset:2048
	ds_read_b64 v[62:63], v79
	v_mov_b32_e32 v64, v5
	v_mov_b32_e32 v65, v5
	v_mfma_f32_16x16x32_bf16 v[26:29], v[66:69], v[38:41], v[26:29]
	ds_read_b128 v[66:69], v242 offset:8192
	ds_read_b128 v[100:103], v242 offset:9216
	v_mfma_f32_16x16x32_bf16 v[30:33], v[80:83], v[38:41], v[30:33]
	ds_read_b128 v[78:81], v242 offset:10240
	ds_read_b128 v[104:107], v242 offset:11264
	ds_read_b128 v[108:111], v213 offset:21504
	ds_read_b128 v[112:115], v213 offset:21568
	v_pk_mul_f32 v[24:25], v[124:125], v[24:25]
	v_mfma_f32_16x16x32_bf16 v[34:37], v[84:87], v[38:41], v[34:37]
	ds_read_b128 v[82:85], v213 offset:21632
	ds_read_b128 v[116:119], v213 offset:21696
	v_pk_mul_f32 v[22:23], v[122:123], v[22:23]
	v_mfma_f32_16x16x32_bf16 v[38:41], v[54:57], v[38:41], v[42:45]
	v_mul_f32_e64 v28, v128, v28
	v_mul_f32_e64 v29, v129, v29
	v_pk_mul_f32 v[26:27], v[126:127], v[26:27]
	v_cvt_pk_bf16_f32 v122, v22, v23
	s_waitcnt lgkmcnt(8)
	v_mfma_f32_16x16x32_bf16 v[74:77], v[74:77], v[62:65], 0
	v_cvt_pk_bf16_f32 v123, v24, v25
	s_nop 0
	v_cvt_pk_bf16_f32 v2, v38, s0
	ds_write_b16 v243, v2 offset:2048
	v_cvt_pk_bf16_f32 v2, v39, s0
	ds_write_b16 v243, v2 offset:2176
	v_cvt_pk_bf16_f32 v2, v40, s0
	v_cvt_pk_bf16_f32 v124, v26, v27
	v_cvt_pk_bf16_f32 v125, v28, v29
	ds_write_b16 v243, v2 offset:2304
	v_cvt_pk_bf16_f32 v2, v41, s0
	v_mfma_f32_16x16x32_bf16 v[50:53], v[50:53], v[122:125], v[74:77]
	ds_write_b16 v243, v2 offset:2432
	v_pk_mul_f32 v[32:33], v[90:91], v[32:33]
	v_pk_mul_f32 v[30:31], v[88:89], v[30:31]
	v_pk_mul_f32 v[36:37], v[132:133], v[36:37]
	v_pk_mul_f32 v[34:35], v[130:131], v[34:35]
	v_cvt_pk_bf16_f32 v126, v30, v31
	v_cvt_pk_bf16_f32 v127, v32, v33
	v_cvt_pk_bf16_f32 v128, v34, v35
	v_cvt_pk_bf16_f32 v129, v36, v37
	s_nop 0
	s_nop 0
	v_mfma_f32_16x16x32_bf16 v[50:53], v[58:61], v[126:129], v[50:53]
	ds_read_b64_tr_b16 v[38:39], v253 offset:12288
	ds_read_b64_tr_b16 v[40:41], v253 offset:13312
	ds_read_b64_tr_b16 v[42:43], v253 offset:14336
	ds_read_b64_tr_b16 v[44:45], v253 offset:15360
	ds_read_b64_tr_b16 v[54:55], v253 offset:12296
	ds_read_b64_tr_b16 v[56:57], v253 offset:13320
	ds_read_b64_tr_b16 v[86:87], v253 offset:14344
	ds_read_b64_tr_b16 v[88:89], v253 offset:15368
	v_bitop3_b32 v2, v135, v134, 12 bitop3:0x36
	ds_read_b64 v[90:91], v202 offset:3584
	ds_read_b64 v[120:121], v202 offset:1536
	v_mfma_f32_16x16x32_bf16 v[58:61], v[70:73], v[122:125], 0
	v_lshl_add_u32 v70, v2, 3, v139
	v_cvt_pk_bf16_f32 v2, v50, v51
	v_cvt_pk_bf16_f32 v3, v52, v53
	v_mov_b32_e32 v4, v5
	v_mfma_f32_16x16x32_bf16 v[58:61], v[92:95], v[126:129], v[58:61]
	v_mov_b32_e32 v92, v5
	v_mov_b32_e32 v93, v5
	v_mov_b32_e32 v122, v5
	v_mfma_f32_16x16x32_bf16 v[50:53], v[96:99], v[2:5], 0
	v_mov_b32_e32 v123, v5
	s_nop 4
	s_nop 1
	v_cvt_pk_bf16_f32 v50, v50, v51
	v_cvt_pk_bf16_f32 v51, v52, v53
	v_mov_b32_e32 v52, v62
	v_mov_b32_e32 v53, v63
	s_nop 0
	s_waitcnt lgkmcnt(14)
	v_mfma_f32_16x16x32_bf16 v[22:25], v[66:69], v[50:53], v[22:25]
	ds_read_b128 v[62:65], v237 offset:3072
	ds_read_b64 v[66:67], v70
	v_mov_b32_e32 v68, v5
	v_mov_b32_e32 v69, v5
	v_mfma_f32_16x16x32_bf16 v[26:29], v[100:103], v[50:53], v[26:29]
	s_nop 1
	s_nop 0
	v_pk_mul_f32 v[24:25], v[110:111], v[24:25]
	v_pk_mul_f32 v[22:23], v[108:109], v[22:23]
	ds_read_b128 v[70:73], v242 offset:12288
	ds_read_b128 v[74:77], v242 offset:13312
	v_mfma_f32_16x16x32_bf16 v[46:49], v[46:49], v[50:53], v[58:61]
	v_mul_f32_e64 v28, v114, v28
	v_mul_f32_e64 v29, v115, v29
	v_pk_mul_f32 v[26:27], v[112:113], v[26:27]
	s_waitcnt lgkmcnt(2)
	v_mfma_f32_16x16x32_bf16 v[58:61], v[90:93], v[66:69], 0
	v_mfma_f32_16x16x32_bf16 v[30:33], v[78:81], v[50:53], v[30:33]
	ds_read_b128 v[78:81], v242 offset:14336
	ds_read_b128 v[94:97], v242 offset:15360
	ds_read_b128 v[98:101], v213 offset:21760
	ds_read_b128 v[124:127], v213 offset:21824
	v_cvt_pk_bf16_f32 v2, v46, s0
	v_mfma_f32_16x16x32_bf16 v[34:37], v[104:107], v[50:53], v[34:37]
	v_cvt_pk_bf16_f32 v50, v22, v23
	v_cvt_pk_bf16_f32 v51, v24, v25
	v_cvt_pk_bf16_f32 v52, v26, v27
	v_cvt_pk_bf16_f32 v53, v28, v29
	v_pk_mul_f32 v[32:33], v[84:85], v[32:33]
	v_pk_mul_f32 v[30:31], v[82:83], v[30:31]
	v_mfma_f32_16x16x32_bf16 v[38:41], v[38:41], v[50:53], v[58:61]
	s_nop 0
	v_mul_f32_e64 v36, v118, v36
	v_mul_f32_e64 v37, v119, v37
	v_pk_mul_f32 v[34:35], v[116:117], v[34:35]
	v_cvt_pk_bf16_f32 v82, v30, v31
	v_cvt_pk_bf16_f32 v83, v32, v33
	v_cvt_pk_bf16_f32 v84, v34, v35
	v_cvt_pk_bf16_f32 v85, v36, v37
	ds_read_b128 v[102:105], v213 offset:21888
	ds_read_b128 v[128:131], v213 offset:21952
	v_mfma_f32_16x16x32_bf16 v[38:41], v[42:45], v[82:85], v[38:41]
	ds_write_b16 v243, v2 offset:4096
	v_cvt_pk_bf16_f32 v2, v47, s0
	v_mfma_f32_16x16x32_bf16 v[42:45], v[54:57], v[50:53], 0
	ds_write_b16 v243, v2 offset:4224
	s_nop 3
	v_cvt_pk_bf16_f32 v2, v38, v39
	v_cvt_pk_bf16_f32 v3, v40, v41
	v_mfma_f32_16x16x32_bf16 v[42:45], v[86:89], v[82:85], v[42:45]
	s_nop 0
	v_mfma_f32_16x16x32_bf16 v[38:41], v[120:123], v[2:5], 0
	v_cvt_pk_bf16_f32 v2, v48, s0
	ds_write_b16 v243, v2 offset:4352
	v_cvt_pk_bf16_f32 v2, v49, s0
	ds_write_b16 v243, v2 offset:4480
	s_nop 2
	s_nop 0
	v_cvt_pk_bf16_f32 v38, v38, v39
	v_cvt_pk_bf16_f32 v39, v40, v41
	v_mov_b32_e32 v40, v66
	v_mov_b32_e32 v41, v67
	s_nop 0
	s_waitcnt lgkmcnt(11)
	v_mfma_f32_16x16x32_bf16 v[22:25], v[70:73], v[38:41], v[22:25]
	s_waitcnt lgkmcnt(10)
	v_mfma_f32_16x16x32_bf16 v[26:29], v[74:77], v[38:41], v[26:29]
	s_waitcnt lgkmcnt(9)
	v_mfma_f32_16x16x32_bf16 v[30:33], v[78:81], v[38:41], v[30:33]
	s_nop 2
	s_waitcnt lgkmcnt(7)
	v_pk_mul_f32 v[24:25], v[100:101], v[24:25]
	v_pk_mul_f32 v[22:23], v[98:99], v[22:23]
	s_waitcnt lgkmcnt(6)
	v_pk_mul_f32 v[28:29], v[126:127], v[28:29]
	v_mfma_f32_16x16x32_bf16 v[34:37], v[94:97], v[38:41], v[34:37]
	v_mul_f32_e64 v26, v124, v26
	v_mul_f32_e64 v27, v125, v27
	s_waitcnt lgkmcnt(5)
	v_pk_mul_f32 v[32:33], v[104:105], v[32:33]
	v_pk_mul_f32 v[30:31], v[102:103], v[30:31]
	v_mfma_f32_16x16x32_bf16 v[38:41], v[62:65], v[38:41], v[42:45]
	s_nop 0
	s_waitcnt lgkmcnt(4)
	v_pk_mul_f32 v[36:37], v[130:131], v[36:37]
	s_nop 4
	v_cvt_pk_bf16_f32 v2, v38, s0
	ds_write_b16 v243, v2 offset:6144
	v_cvt_pk_bf16_f32 v2, v39, s0
	ds_write_b16 v243, v2 offset:6272
	v_cvt_pk_bf16_f32 v2, v40, s0
	v_pk_mul_f32 v[34:35], v[128:129], v[34:35]
	ds_write_b16 v243, v2 offset:6400
	v_cvt_pk_bf16_f32 v2, v41, s0
	ds_write_b16 v243, v2 offset:6528
	s_branch .LBB0_540
